# layer-1 adaLN GEMV items moved from phase 0 to the idle time of phase 2's two-unit workgroups; phase-0 norm rows back to an even split
# speedup vs baseline: 1.0534x; 1.0040x over previous
.LBB0_1101:
	s_or_b64 exec, exec, s[0:1]
	v_readlane_b32 s36, v254, 32
	s_movk_i32 s99, 0x17f
	s_cmpk_lg_u32 s24, 0x100
	s_cbranch_scc1 .Lal_b0
	s_movk_i32 s99, 0xbf
.Lal_b0:
	s_cmp_gt_i32 s56, s99
	v_lshrrev_b32_e32 v44, 3, v224
	v_cmp_eq_u32_e32 vcc, 0, v192
	v_readlane_b32 s37, v254, 33
	s_waitcnt vmcnt(0) lgkmcnt(0)
	s_barrier
	s_cbranch_scc1 .LBB0_1113
	v_lshlrev_b32_e32 v0, 2, v224
	v_and_b32_e32 v1, 64, v219
	v_and_b32_e32 v4, 28, v0
	v_xor_b32_e32 v0, 8, v219
	v_add_u32_e32 v1, 64, v1
	v_cmp_lt_i32_e64 s[0:1], v0, v1
	v_and_b32_e32 v2, 31, v192
	v_lshl_add_u32 v5, v224, 4, 0
	v_cndmask_b32_e64 v0, v219, v0, s[0:1]
	v_lshlrev_b32_e32 v3, 2, v0
	v_xor_b32_e32 v0, 16, v219
	v_cmp_lt_i32_e64 s[0:1], v0, v1
	v_lshl_add_u32 v6, v2, 2, 0
	v_cmp_gt_u32_e64 s[38:39], 8, v224
	v_cndmask_b32_e64 v0, v219, v0, s[0:1]
	v_lshlrev_b32_e32 v45, 2, v0
	v_xor_b32_e32 v0, 32, v219
	v_cmp_lt_i32_e64 s[0:1], v0, v1
	v_lshlrev_b32_e32 v178, 2, v4
	s_mov_b32 s22, s56
	v_cndmask_b32_e64 v0, v219, v0, s[0:1]
	s_movk_i32 s0, 0xa0
	v_readlane_b32 s1, v255, 5
	v_lshlrev_b32_e32 v46, 2, v0
	v_cmp_gt_i32_e64 s[40:41], s0, v192
	v_ashrrev_i32_e32 v0, 5, v192
	s_mul_i32 s0, s1, 0x280
	v_lshl_or_b32 v47, s1, 7, v44
	s_lshl_b32 s1, s1, 9
	v_lshlrev_b32_e32 v7, 7, v0
	s_add_i32 s1, s1, 0
	v_ashrrev_i32_e32 v1, 31, v0
	v_lshl_add_u32 v48, v44, 2, s1
	v_add_u32_e32 v49, s0, v5
	v_add_u32_e32 v50, v6, v7
	s_branch .LBB0_1104
.LBB0_1103:
	s_or_b64 exec, exec, s[2:3]
	s_add_i32 s22, s22, s24
	s_cmp_gt_i32 s22, s99
	s_cbranch_scc1 .LBB0_1113

.LBB0_1141:
	global_load_dwordx4 v[32:35], v30, s[40:41]
	global_load_dwordx4 v[36:39], v30, s[40:41] offset:1024
	global_load_dwordx4 v[16:19], v30, s[40:41] offset:3072
	global_load_dwordx4 v[40:43], v30, s[40:41] offset:2048
	s_lshr_b32 s24, s26, 10
	s_add_i32 s24, s24, 1
	s_and_b64 s[34:35], s[38:39], exec
	s_cselect_b32 s24, 0, s24
	v_mad_u64_u32 v[52:53], s[34:35], s24, v223, v[20:21]
	v_add_co_u32_e32 v54, vcc, s33, v52
	s_lshl_b64 s[0:1], s[0:1], 11
	s_nop 0
	v_addc_co_u32_e32 v55, vcc, 0, v53, vcc
	global_load_dwordx4 v[44:47], v[54:55], off
	global_load_dwordx4 v[48:51], v[52:53], off
	s_branch .Ln1_orig

	s_cmpk_lt_i32 s2, 0x1800
	s_cbranch_scc1 .Ln1_orig
	s_cmp_lt_u32 s56, 128
	s_cbranch_scc1 .Ln1_stop
	s_add_u32 s2, s2, 0x400
	s_addc_u32 s3, s3, 0
	s_branch .Ln1_next

.Ltq_exit:
	s_waitcnt vmcnt(0) lgkmcnt(0)
	s_mov_b64 s[84:85], s[60:61]
	v_readlane_b32 s0, v255, 24
	v_readlane_b32 s1, v255, 25
	v_readlane_b32 s2, v255, 26
	v_readlane_b32 s3, v255, 27
	v_readlane_b32 s20, v255, 28
	v_readlane_b32 s21, v255, 29
	v_readlane_b32 s22, v255, 30
	v_readlane_b32 s23, v255, 31
	v_readlane_b32 s26, v255, 32
	v_readlane_b32 s33, v255, 33
	v_readlane_b32 s34, v255, 34
	v_readlane_b32 s35, v255, 35
	v_readlane_b32 s36, v255, 36
	v_readlane_b32 s37, v255, 37
	v_readlane_b32 s38, v255, 38
	v_readlane_b32 s39, v255, 39
	v_readlane_b32 s40, v255, 40
	v_readlane_b32 s41, v255, 41
	v_readlane_b32 s42, v255, 42
	v_readlane_b32 s43, v255, 43
	v_readlane_b32 s56, v255, 44
	v_readlane_b32 s57, v255, 45
	v_readlane_b32 s58, v255, 46
	v_readlane_b32 s60, v255, 47
	v_readlane_b32 s61, v255, 48
	v_readlane_b32 s80, v255, 49
	v_readlane_b32 s81, v255, 50
	v_readlane_b32 s82, v255, 51
	v_readlane_b32 s83, v255, 52
	v_readlane_b32 s86, v255, 53
	v_readlane_b32 s87, v255, 54
	v_readlane_b32 s88, v255, 55
	v_readlane_b32 s89, v255, 56
	v_readlane_b32 s90, v255, 57
	v_readlane_b32 s91, v255, 58
	v_readlane_b32 s92, v255, 59
	v_readlane_b32 s93, v255, 60
	v_readlane_b32 s94, v255, 61
	v_readlane_b32 s95, v255, 62
	s_nop 4
	s_barrier
	v_writelane_b32 v255, s0, 24
	v_writelane_b32 v255, s1, 25
	v_writelane_b32 v255, s2, 26
	v_writelane_b32 v255, s3, 27
	v_writelane_b32 v255, s20, 28
	v_writelane_b32 v255, s21, 29
	v_writelane_b32 v255, s22, 30
	v_writelane_b32 v255, s23, 31
	v_writelane_b32 v255, s26, 32
	v_writelane_b32 v255, s34, 33
	v_writelane_b32 v255, s35, 34
	v_writelane_b32 v255, s36, 35
	v_writelane_b32 v255, s37, 36
	v_writelane_b32 v255, s38, 37
	v_writelane_b32 v255, s39, 38
	v_writelane_b32 v255, s40, 39
	v_writelane_b32 v255, s41, 40
	v_writelane_b32 v255, s44, 41
	v_writelane_b32 v255, s45, 42
	v_writelane_b32 v255, s56, 43
	v_readlane_b32 s56, v255, 6
	s_nop 3
	s_movk_i32 s0, 0x1400
	v_cmp_gt_i32_e32 vcc, s0, v192
	s_and_saveexec_b64 s[0:1], vcc
	v_readlane_b32 s44, v254, 34
	s_movk_i32 s26, 0x3ff
	v_readlane_b32 s45, v254, 35
	s_cbranch_execz .Lal_1101

	v_lshl_add_u32 v2, v192, 2, 0
	s_mov_b64 s[2:3], 0
	v_mov_b32_e32 v3, v192
	s_branch .Lal_1097

.Lal_1097:

	v_and_b32_e32 v4, 0x3ff, v3
	v_cmp_lt_u32_e32 vcc, s26, v3

	s_and_saveexec_b64 s[20:21], vcc
	s_xor_b64 s[20:21], exec, s[20:21]

	s_movk_i32 s22, 0xfc00
	v_and_or_b32 v0, v3, s22, v4
	v_add_u32_e32 v0, 0xfffffc00, v0
	v_ashrrev_i32_e32 v1, 31, v0
	v_lshl_add_u64 v[0:1], v[0:1], 2, s[12:13]


	s_andn2_saveexec_b64 s[20:21], s[20:21]
	s_cbranch_execz .Lal_1096

	v_lshlrev_b32_e32 v178, 2, v4
	v_lshl_add_u64 v[0:1], s[14:15], 0, v[178:179]
	s_branch .Lal_1096
.Lal_1101:
	s_or_b64 exec, exec, s[0:1]
	v_readlane_b32 s36, v254, 32
	s_cmpk_gt_i32 s56, 0x17f
	v_lshrrev_b32_e32 v44, 3, v224
	v_cmp_eq_u32_e32 vcc, 0, v192
	v_readlane_b32 s37, v254, 33
	s_waitcnt vmcnt(0) lgkmcnt(0)
	s_barrier
	s_cbranch_scc1 .Lal_exit

	v_lshlrev_b32_e32 v0, 2, v224
	v_and_b32_e32 v1, 64, v219
	v_and_b32_e32 v4, 28, v0
	v_xor_b32_e32 v0, 8, v219
	v_add_u32_e32 v1, 64, v1
	v_cmp_lt_i32_e64 s[0:1], v0, v1
	v_and_b32_e32 v2, 31, v192
	v_lshl_add_u32 v5, v224, 4, 0
	v_cndmask_b32_e64 v0, v219, v0, s[0:1]
	v_lshlrev_b32_e32 v3, 2, v0
	v_xor_b32_e32 v0, 16, v219
	v_cmp_lt_i32_e64 s[0:1], v0, v1
	v_lshl_add_u32 v6, v2, 2, 0
	v_cmp_gt_u32_e64 s[38:39], 8, v224
	v_cndmask_b32_e64 v0, v219, v0, s[0:1]
	v_lshlrev_b32_e32 v45, 2, v0
	v_xor_b32_e32 v0, 32, v219
	v_cmp_lt_i32_e64 s[0:1], v0, v1
	v_lshlrev_b32_e32 v178, 2, v4
	s_add_i32 s22, s56, 0x80
	v_cndmask_b32_e64 v0, v219, v0, s[0:1]
	s_movk_i32 s0, 0xa0
	v_readlane_b32 s1, v255, 5
	v_lshlrev_b32_e32 v46, 2, v0
	v_cmp_gt_i32_e64 s[40:41], s0, v192
	v_ashrrev_i32_e32 v0, 5, v192
	s_mul_i32 s0, s1, 0x280
	v_lshl_or_b32 v47, s1, 7, v44
	s_lshl_b32 s1, s1, 9
	v_lshlrev_b32_e32 v7, 7, v0
	s_add_i32 s1, s1, 0
	v_ashrrev_i32_e32 v1, 31, v0
	v_lshl_add_u32 v48, v44, 2, s1
	v_add_u32_e32 v49, s0, v5
	v_add_u32_e32 v50, v6, v7
	s_branch .Lal_1104

.Lal_1104:


	s_mul_hi_i32 s0, s22, 0x2aaaaaab
	s_lshr_b32 s1, s0, 31
	s_ashr_i32 s0, s0, 5
	s_add_i32 s21, s0, s1
	s_mul_i32 s0, s21, 0xc0
	s_sub_i32 s20, s22, s0
	s_lshl_b32 s0, s20, 5
	s_mul_i32 s2, s21, 0x1800000
	s_mul_hi_i32 s1, s21, 0x1800000
	s_add_u32 s23, s16, s2
	s_addc_u32 s26, s17, s1
	s_ashr_i32 s1, s0, 31
	s_lshl_b64 s[2:3], s[0:1], 2
	s_add_u32 s2, s23, s2
	s_addc_u32 s3, s26, s3
	v_mov_b32_e32 v24, 0
	v_lshl_add_u64 v[20:21], s[2:3], 0, v[178:179]
	s_mov_b32 s2, 0
	v_mov_b32_e32 v26, v48
	v_mov_b32_e32 v25, v24
	v_mov_b32_e32 v22, v24
	v_mov_b32_e32 v23, v24
	v_mov_b32_e32 v18, v24
	v_mov_b32_e32 v19, v24
	v_mov_b32_e32 v16, v24
	v_mov_b32_e32 v17, v24
	v_mov_b32_e32 v14, v24
	v_mov_b32_e32 v15, v24
	v_mov_b32_e32 v12, v24
	v_mov_b32_e32 v13, v24
	v_mov_b32_e32 v10, v24
	v_mov_b32_e32 v11, v24
	v_mov_b32_e32 v8, v24
	v_mov_b32_e32 v9, v24
	v_mov_b32_e32 v6, v24
	v_mov_b32_e32 v7, v24
	v_mov_b32_e32 v4, v24
	v_mov_b32_e32 v5, v24
.Lal_1105:
	v_add_u32_e32 v27, 0, v47
	v_mad_i64_i32 v[28:29], s[34:35], v27, s25, v[20:21]
	global_load_dwordx4 v[92:95], v[28:29], off nt
	v_add_u32_e32 v27, 8, v47
	v_mad_i64_i32 v[28:29], s[34:35], v27, s25, v[20:21]
	global_load_dwordx4 v[96:99], v[28:29], off nt
	v_add_u32_e32 v27, 16, v47
	v_mad_i64_i32 v[28:29], s[34:35], v27, s25, v[20:21]
	global_load_dwordx4 v[100:103], v[28:29], off nt
	v_add_u32_e32 v27, 24, v47
	v_mad_i64_i32 v[28:29], s[34:35], v27, s25, v[20:21]
	global_load_dwordx4 v[104:107], v[28:29], off nt
	v_add_u32_e32 v27, 32, v47
	v_mad_i64_i32 v[28:29], s[34:35], v27, s25, v[20:21]
	global_load_dwordx4 v[108:111], v[28:29], off nt
	v_add_u32_e32 v27, 40, v47
	v_mad_i64_i32 v[28:29], s[34:35], v27, s25, v[20:21]
	global_load_dwordx4 v[112:115], v[28:29], off nt
	v_add_u32_e32 v27, 48, v47
	v_mad_i64_i32 v[28:29], s[34:35], v27, s25, v[20:21]
	global_load_dwordx4 v[116:119], v[28:29], off nt
	v_add_u32_e32 v27, 56, v47
	v_mad_i64_i32 v[28:29], s[34:35], v27, s25, v[20:21]
	global_load_dwordx4 v[120:123], v[28:29], off nt
	v_add_u32_e32 v27, 64, v47
	v_mad_i64_i32 v[28:29], s[34:35], v27, s25, v[20:21]
	global_load_dwordx4 v[124:127], v[28:29], off nt
	v_add_u32_e32 v27, 72, v47
	v_mad_i64_i32 v[28:29], s[34:35], v27, s25, v[20:21]
	global_load_dwordx4 v[128:131], v[28:29], off nt
	v_add_u32_e32 v27, 80, v47
	v_mad_i64_i32 v[28:29], s[34:35], v27, s25, v[20:21]
	global_load_dwordx4 v[132:135], v[28:29], off nt
	v_add_u32_e32 v27, 88, v47
	v_mad_i64_i32 v[28:29], s[34:35], v27, s25, v[20:21]
	global_load_dwordx4 v[136:139], v[28:29], off nt
	v_add_u32_e32 v27, 96, v47
	v_mad_i64_i32 v[28:29], s[34:35], v27, s25, v[20:21]
	global_load_dwordx4 v[140:143], v[28:29], off nt
	v_add_u32_e32 v27, 104, v47
	v_mad_i64_i32 v[28:29], s[34:35], v27, s25, v[20:21]
	global_load_dwordx4 v[144:147], v[28:29], off nt
	v_add_u32_e32 v27, 112, v47
	v_mad_i64_i32 v[28:29], s[34:35], v27, s25, v[20:21]
	global_load_dwordx4 v[148:151], v[28:29], off nt
	v_add_u32_e32 v27, 120, v47
	v_mad_i64_i32 v[28:29], s[34:35], v27, s25, v[20:21]
	global_load_dwordx4 v[152:155], v[28:29], off nt
	ds_read2_b32 v[52:53], v26 offset1:8
	v_add_u32_e32 v27, 0x1000, v26
	v_add_u32_e32 v68, 0x3000, v26
	v_add_u32_e32 v70, 0x4000, v26
	v_add_u32_e32 v51, 0x2000, v26
	ds_read2_b32 v[54:55], v26 offset0:16 offset1:24
	ds_read2_b32 v[56:57], v27 offset1:8
	ds_read2_b32 v[58:59], v51 offset1:8
	ds_read2_b32 v[60:61], v68 offset1:8
	ds_read2_b32 v[62:63], v70 offset1:8
	ds_read2_b32 v[64:65], v27 offset0:16 offset1:24
	ds_read2_b32 v[66:67], v51 offset0:16 offset1:24
	ds_read2_b32 v[68:69], v68 offset0:16 offset1:24
	ds_read2_b32 v[70:71], v70 offset0:16 offset1:24
	s_waitcnt lgkmcnt(9)
	v_mov_b32_e32 v72, v53
	s_waitcnt lgkmcnt(7)
	v_mov_b32_e32 v76, v57
	s_waitcnt lgkmcnt(6)
	v_mov_b32_e32 v78, v59
	s_waitcnt lgkmcnt(5)
	v_mov_b32_e32 v80, v61
	s_waitcnt lgkmcnt(4)
	v_mov_b32_e32 v82, v63
	v_mov_b32_e32 v74, v55
	s_waitcnt lgkmcnt(3)
	v_mov_b32_e32 v84, v65
	s_waitcnt lgkmcnt(2)
	v_mov_b32_e32 v86, v67
	s_waitcnt lgkmcnt(1)
	v_mov_b32_e32 v88, v69
	s_waitcnt lgkmcnt(0)
	v_mov_b32_e32 v90, v71
	v_add_u32_e32 v26, 0x80, v26
	s_waitcnt vmcnt(15)
	v_pk_fma_f32 v[24:25], v[92:93], v[52:53], v[24:25] op_sel_hi:[1,0,1]
	v_pk_fma_f32 v[22:23], v[94:95], v[52:53], v[22:23] op_sel_hi:[1,0,1]
	v_pk_fma_f32 v[18:19], v[92:93], v[56:57], v[18:19] op_sel_hi:[1,0,1]
	v_pk_fma_f32 v[16:17], v[94:95], v[56:57], v[16:17] op_sel_hi:[1,0,1]
	v_pk_fma_f32 v[14:15], v[92:93], v[58:59], v[14:15] op_sel_hi:[1,0,1]
	v_pk_fma_f32 v[12:13], v[94:95], v[58:59], v[12:13] op_sel_hi:[1,0,1]
	v_pk_fma_f32 v[10:11], v[92:93], v[60:61], v[10:11] op_sel_hi:[1,0,1]
	v_pk_fma_f32 v[8:9], v[94:95], v[60:61], v[8:9] op_sel_hi:[1,0,1]
	v_pk_fma_f32 v[6:7], v[92:93], v[62:63], v[6:7] op_sel_hi:[1,0,1]
	v_pk_fma_f32 v[4:5], v[94:95], v[62:63], v[4:5] op_sel_hi:[1,0,1]
	s_waitcnt vmcnt(14)
	v_pk_fma_f32 v[22:23], v[98:99], v[72:73], v[22:23] op_sel_hi:[1,0,1]
	v_pk_fma_f32 v[24:25], v[96:97], v[72:73], v[24:25] op_sel_hi:[1,0,1]
	v_pk_fma_f32 v[16:17], v[98:99], v[76:77], v[16:17] op_sel_hi:[1,0,1]
	v_pk_fma_f32 v[18:19], v[96:97], v[76:77], v[18:19] op_sel_hi:[1,0,1]
	v_pk_fma_f32 v[12:13], v[98:99], v[78:79], v[12:13] op_sel_hi:[1,0,1]
	v_pk_fma_f32 v[14:15], v[96:97], v[78:79], v[14:15] op_sel_hi:[1,0,1]
	v_pk_fma_f32 v[8:9], v[98:99], v[80:81], v[8:9] op_sel_hi:[1,0,1]
	v_pk_fma_f32 v[10:11], v[96:97], v[80:81], v[10:11] op_sel_hi:[1,0,1]
	v_pk_fma_f32 v[4:5], v[98:99], v[82:83], v[4:5] op_sel_hi:[1,0,1]
	v_pk_fma_f32 v[6:7], v[96:97], v[82:83], v[6:7] op_sel_hi:[1,0,1]
	s_waitcnt vmcnt(13)
	v_pk_fma_f32 v[24:25], v[100:101], v[54:55], v[24:25] op_sel_hi:[1,0,1]
	v_pk_fma_f32 v[22:23], v[102:103], v[54:55], v[22:23] op_sel_hi:[1,0,1]
	v_pk_fma_f32 v[18:19], v[100:101], v[64:65], v[18:19] op_sel_hi:[1,0,1]
	v_pk_fma_f32 v[16:17], v[102:103], v[64:65], v[16:17] op_sel_hi:[1,0,1]
	v_pk_fma_f32 v[14:15], v[100:101], v[66:67], v[14:15] op_sel_hi:[1,0,1]
	v_pk_fma_f32 v[12:13], v[102:103], v[66:67], v[12:13] op_sel_hi:[1,0,1]
	v_pk_fma_f32 v[10:11], v[100:101], v[68:69], v[10:11] op_sel_hi:[1,0,1]
	v_pk_fma_f32 v[8:9], v[102:103], v[68:69], v[8:9] op_sel_hi:[1,0,1]
	v_pk_fma_f32 v[6:7], v[100:101], v[70:71], v[6:7] op_sel_hi:[1,0,1]
	v_pk_fma_f32 v[4:5], v[102:103], v[70:71], v[4:5] op_sel_hi:[1,0,1]
	s_waitcnt vmcnt(12)
	v_pk_fma_f32 v[22:23], v[106:107], v[74:75], v[22:23] op_sel_hi:[1,0,1]
	v_pk_fma_f32 v[24:25], v[104:105], v[74:75], v[24:25] op_sel_hi:[1,0,1]
	v_pk_fma_f32 v[16:17], v[106:107], v[84:85], v[16:17] op_sel_hi:[1,0,1]
	v_pk_fma_f32 v[18:19], v[104:105], v[84:85], v[18:19] op_sel_hi:[1,0,1]
	v_pk_fma_f32 v[12:13], v[106:107], v[86:87], v[12:13] op_sel_hi:[1,0,1]
	v_pk_fma_f32 v[14:15], v[104:105], v[86:87], v[14:15] op_sel_hi:[1,0,1]
	v_pk_fma_f32 v[8:9], v[106:107], v[88:89], v[8:9] op_sel_hi:[1,0,1]
	v_pk_fma_f32 v[10:11], v[104:105], v[88:89], v[10:11] op_sel_hi:[1,0,1]
	v_pk_fma_f32 v[4:5], v[106:107], v[90:91], v[4:5] op_sel_hi:[1,0,1]
	v_pk_fma_f32 v[6:7], v[104:105], v[90:91], v[6:7] op_sel_hi:[1,0,1]
	ds_read2_b32 v[52:53], v26 offset1:8
	v_add_u32_e32 v27, 0x1000, v26
	v_add_u32_e32 v68, 0x3000, v26
	v_add_u32_e32 v70, 0x4000, v26
	v_add_u32_e32 v51, 0x2000, v26
	ds_read2_b32 v[54:55], v26 offset0:16 offset1:24
	ds_read2_b32 v[56:57], v27 offset1:8
	ds_read2_b32 v[58:59], v51 offset1:8
	ds_read2_b32 v[60:61], v68 offset1:8
	ds_read2_b32 v[62:63], v70 offset1:8
	ds_read2_b32 v[64:65], v27 offset0:16 offset1:24
	ds_read2_b32 v[66:67], v51 offset0:16 offset1:24
	ds_read2_b32 v[68:69], v68 offset0:16 offset1:24
	ds_read2_b32 v[70:71], v70 offset0:16 offset1:24
	s_waitcnt lgkmcnt(9)
	v_mov_b32_e32 v72, v53
	s_waitcnt lgkmcnt(7)
	v_mov_b32_e32 v76, v57
	s_waitcnt lgkmcnt(6)
	v_mov_b32_e32 v78, v59
	s_waitcnt lgkmcnt(5)
	v_mov_b32_e32 v80, v61
	s_waitcnt lgkmcnt(4)
	v_mov_b32_e32 v82, v63
	v_mov_b32_e32 v74, v55
	s_waitcnt lgkmcnt(3)
	v_mov_b32_e32 v84, v65
	s_waitcnt lgkmcnt(2)
	v_mov_b32_e32 v86, v67
	s_waitcnt lgkmcnt(1)
	v_mov_b32_e32 v88, v69
	s_waitcnt lgkmcnt(0)
	v_mov_b32_e32 v90, v71
	v_add_u32_e32 v26, 0x80, v26
	s_waitcnt vmcnt(11)
	v_pk_fma_f32 v[24:25], v[108:109], v[52:53], v[24:25] op_sel_hi:[1,0,1]
	v_pk_fma_f32 v[22:23], v[110:111], v[52:53], v[22:23] op_sel_hi:[1,0,1]
	v_pk_fma_f32 v[18:19], v[108:109], v[56:57], v[18:19] op_sel_hi:[1,0,1]
	v_pk_fma_f32 v[16:17], v[110:111], v[56:57], v[16:17] op_sel_hi:[1,0,1]
	v_pk_fma_f32 v[14:15], v[108:109], v[58:59], v[14:15] op_sel_hi:[1,0,1]
	v_pk_fma_f32 v[12:13], v[110:111], v[58:59], v[12:13] op_sel_hi:[1,0,1]
	v_pk_fma_f32 v[10:11], v[108:109], v[60:61], v[10:11] op_sel_hi:[1,0,1]
	v_pk_fma_f32 v[8:9], v[110:111], v[60:61], v[8:9] op_sel_hi:[1,0,1]
	v_pk_fma_f32 v[6:7], v[108:109], v[62:63], v[6:7] op_sel_hi:[1,0,1]
	v_pk_fma_f32 v[4:5], v[110:111], v[62:63], v[4:5] op_sel_hi:[1,0,1]
	s_waitcnt vmcnt(10)
	v_pk_fma_f32 v[22:23], v[114:115], v[72:73], v[22:23] op_sel_hi:[1,0,1]
	v_pk_fma_f32 v[24:25], v[112:113], v[72:73], v[24:25] op_sel_hi:[1,0,1]
	v_pk_fma_f32 v[16:17], v[114:115], v[76:77], v[16:17] op_sel_hi:[1,0,1]
	v_pk_fma_f32 v[18:19], v[112:113], v[76:77], v[18:19] op_sel_hi:[1,0,1]
	v_pk_fma_f32 v[12:13], v[114:115], v[78:79], v[12:13] op_sel_hi:[1,0,1]
	v_pk_fma_f32 v[14:15], v[112:113], v[78:79], v[14:15] op_sel_hi:[1,0,1]
	v_pk_fma_f32 v[8:9], v[114:115], v[80:81], v[8:9] op_sel_hi:[1,0,1]
	v_pk_fma_f32 v[10:11], v[112:113], v[80:81], v[10:11] op_sel_hi:[1,0,1]
	v_pk_fma_f32 v[4:5], v[114:115], v[82:83], v[4:5] op_sel_hi:[1,0,1]
	v_pk_fma_f32 v[6:7], v[112:113], v[82:83], v[6:7] op_sel_hi:[1,0,1]
	s_waitcnt vmcnt(9)
	v_pk_fma_f32 v[24:25], v[116:117], v[54:55], v[24:25] op_sel_hi:[1,0,1]
	v_pk_fma_f32 v[22:23], v[118:119], v[54:55], v[22:23] op_sel_hi:[1,0,1]
	v_pk_fma_f32 v[18:19], v[116:117], v[64:65], v[18:19] op_sel_hi:[1,0,1]
	v_pk_fma_f32 v[16:17], v[118:119], v[64:65], v[16:17] op_sel_hi:[1,0,1]
	v_pk_fma_f32 v[14:15], v[116:117], v[66:67], v[14:15] op_sel_hi:[1,0,1]
	v_pk_fma_f32 v[12:13], v[118:119], v[66:67], v[12:13] op_sel_hi:[1,0,1]
	v_pk_fma_f32 v[10:11], v[116:117], v[68:69], v[10:11] op_sel_hi:[1,0,1]
	v_pk_fma_f32 v[8:9], v[118:119], v[68:69], v[8:9] op_sel_hi:[1,0,1]
	v_pk_fma_f32 v[6:7], v[116:117], v[70:71], v[6:7] op_sel_hi:[1,0,1]
	v_pk_fma_f32 v[4:5], v[118:119], v[70:71], v[4:5] op_sel_hi:[1,0,1]
	s_waitcnt vmcnt(8)
	v_pk_fma_f32 v[22:23], v[122:123], v[74:75], v[22:23] op_sel_hi:[1,0,1]
	v_pk_fma_f32 v[24:25], v[120:121], v[74:75], v[24:25] op_sel_hi:[1,0,1]
	v_pk_fma_f32 v[16:17], v[122:123], v[84:85], v[16:17] op_sel_hi:[1,0,1]
	v_pk_fma_f32 v[18:19], v[120:121], v[84:85], v[18:19] op_sel_hi:[1,0,1]
	v_pk_fma_f32 v[12:13], v[122:123], v[86:87], v[12:13] op_sel_hi:[1,0,1]
	v_pk_fma_f32 v[14:15], v[120:121], v[86:87], v[14:15] op_sel_hi:[1,0,1]
	v_pk_fma_f32 v[8:9], v[122:123], v[88:89], v[8:9] op_sel_hi:[1,0,1]
	v_pk_fma_f32 v[10:11], v[120:121], v[88:89], v[10:11] op_sel_hi:[1,0,1]
	v_pk_fma_f32 v[4:5], v[122:123], v[90:91], v[4:5] op_sel_hi:[1,0,1]
	v_pk_fma_f32 v[6:7], v[120:121], v[90:91], v[6:7] op_sel_hi:[1,0,1]
	ds_read2_b32 v[52:53], v26 offset1:8
	v_add_u32_e32 v27, 0x1000, v26
	v_add_u32_e32 v68, 0x3000, v26
	v_add_u32_e32 v70, 0x4000, v26
	v_add_u32_e32 v51, 0x2000, v26
	ds_read2_b32 v[54:55], v26 offset0:16 offset1:24
	ds_read2_b32 v[56:57], v27 offset1:8
	ds_read2_b32 v[58:59], v51 offset1:8
	ds_read2_b32 v[60:61], v68 offset1:8
	ds_read2_b32 v[62:63], v70 offset1:8
	ds_read2_b32 v[64:65], v27 offset0:16 offset1:24
	ds_read2_b32 v[66:67], v51 offset0:16 offset1:24
	ds_read2_b32 v[68:69], v68 offset0:16 offset1:24
	ds_read2_b32 v[70:71], v70 offset0:16 offset1:24
	s_waitcnt lgkmcnt(9)
	v_mov_b32_e32 v72, v53
	s_waitcnt lgkmcnt(7)
	v_mov_b32_e32 v76, v57
	s_waitcnt lgkmcnt(6)
	v_mov_b32_e32 v78, v59
	s_waitcnt lgkmcnt(5)
	v_mov_b32_e32 v80, v61
	s_waitcnt lgkmcnt(4)
	v_mov_b32_e32 v82, v63
	v_mov_b32_e32 v74, v55
	s_waitcnt lgkmcnt(3)
	v_mov_b32_e32 v84, v65
	s_waitcnt lgkmcnt(2)
	v_mov_b32_e32 v86, v67
	s_waitcnt lgkmcnt(1)
	v_mov_b32_e32 v88, v69
	s_waitcnt lgkmcnt(0)
	v_mov_b32_e32 v90, v71
	v_add_u32_e32 v26, 0x80, v26
	s_waitcnt vmcnt(7)
	v_pk_fma_f32 v[24:25], v[124:125], v[52:53], v[24:25] op_sel_hi:[1,0,1]
	v_pk_fma_f32 v[22:23], v[126:127], v[52:53], v[22:23] op_sel_hi:[1,0,1]
	v_pk_fma_f32 v[18:19], v[124:125], v[56:57], v[18:19] op_sel_hi:[1,0,1]
	v_pk_fma_f32 v[16:17], v[126:127], v[56:57], v[16:17] op_sel_hi:[1,0,1]
	v_pk_fma_f32 v[14:15], v[124:125], v[58:59], v[14:15] op_sel_hi:[1,0,1]
	v_pk_fma_f32 v[12:13], v[126:127], v[58:59], v[12:13] op_sel_hi:[1,0,1]
	v_pk_fma_f32 v[10:11], v[124:125], v[60:61], v[10:11] op_sel_hi:[1,0,1]
	v_pk_fma_f32 v[8:9], v[126:127], v[60:61], v[8:9] op_sel_hi:[1,0,1]
	v_pk_fma_f32 v[6:7], v[124:125], v[62:63], v[6:7] op_sel_hi:[1,0,1]
	v_pk_fma_f32 v[4:5], v[126:127], v[62:63], v[4:5] op_sel_hi:[1,0,1]
	s_waitcnt vmcnt(6)
	v_pk_fma_f32 v[22:23], v[130:131], v[72:73], v[22:23] op_sel_hi:[1,0,1]
	v_pk_fma_f32 v[24:25], v[128:129], v[72:73], v[24:25] op_sel_hi:[1,0,1]
	v_pk_fma_f32 v[16:17], v[130:131], v[76:77], v[16:17] op_sel_hi:[1,0,1]
	v_pk_fma_f32 v[18:19], v[128:129], v[76:77], v[18:19] op_sel_hi:[1,0,1]
	v_pk_fma_f32 v[12:13], v[130:131], v[78:79], v[12:13] op_sel_hi:[1,0,1]
	v_pk_fma_f32 v[14:15], v[128:129], v[78:79], v[14:15] op_sel_hi:[1,0,1]
	v_pk_fma_f32 v[8:9], v[130:131], v[80:81], v[8:9] op_sel_hi:[1,0,1]
	v_pk_fma_f32 v[10:11], v[128:129], v[80:81], v[10:11] op_sel_hi:[1,0,1]
	v_pk_fma_f32 v[4:5], v[130:131], v[82:83], v[4:5] op_sel_hi:[1,0,1]
	v_pk_fma_f32 v[6:7], v[128:129], v[82:83], v[6:7] op_sel_hi:[1,0,1]
	s_waitcnt vmcnt(5)
	v_pk_fma_f32 v[24:25], v[132:133], v[54:55], v[24:25] op_sel_hi:[1,0,1]
	v_pk_fma_f32 v[22:23], v[134:135], v[54:55], v[22:23] op_sel_hi:[1,0,1]
	v_pk_fma_f32 v[18:19], v[132:133], v[64:65], v[18:19] op_sel_hi:[1,0,1]
	v_pk_fma_f32 v[16:17], v[134:135], v[64:65], v[16:17] op_sel_hi:[1,0,1]
	v_pk_fma_f32 v[14:15], v[132:133], v[66:67], v[14:15] op_sel_hi:[1,0,1]
	v_pk_fma_f32 v[12:13], v[134:135], v[66:67], v[12:13] op_sel_hi:[1,0,1]
	v_pk_fma_f32 v[10:11], v[132:133], v[68:69], v[10:11] op_sel_hi:[1,0,1]
	v_pk_fma_f32 v[8:9], v[134:135], v[68:69], v[8:9] op_sel_hi:[1,0,1]
	v_pk_fma_f32 v[6:7], v[132:133], v[70:71], v[6:7] op_sel_hi:[1,0,1]
	v_pk_fma_f32 v[4:5], v[134:135], v[70:71], v[4:5] op_sel_hi:[1,0,1]
	s_waitcnt vmcnt(4)
	v_pk_fma_f32 v[22:23], v[138:139], v[74:75], v[22:23] op_sel_hi:[1,0,1]
	v_pk_fma_f32 v[24:25], v[136:137], v[74:75], v[24:25] op_sel_hi:[1,0,1]
	v_pk_fma_f32 v[16:17], v[138:139], v[84:85], v[16:17] op_sel_hi:[1,0,1]
	v_pk_fma_f32 v[18:19], v[136:137], v[84:85], v[18:19] op_sel_hi:[1,0,1]
	v_pk_fma_f32 v[12:13], v[138:139], v[86:87], v[12:13] op_sel_hi:[1,0,1]
	v_pk_fma_f32 v[14:15], v[136:137], v[86:87], v[14:15] op_sel_hi:[1,0,1]
	v_pk_fma_f32 v[8:9], v[138:139], v[88:89], v[8:9] op_sel_hi:[1,0,1]
	v_pk_fma_f32 v[10:11], v[136:137], v[88:89], v[10:11] op_sel_hi:[1,0,1]
	v_pk_fma_f32 v[4:5], v[138:139], v[90:91], v[4:5] op_sel_hi:[1,0,1]
	v_pk_fma_f32 v[6:7], v[136:137], v[90:91], v[6:7] op_sel_hi:[1,0,1]
	ds_read2_b32 v[52:53], v26 offset1:8
	v_add_u32_e32 v27, 0x1000, v26
	v_add_u32_e32 v68, 0x3000, v26
	v_add_u32_e32 v70, 0x4000, v26
	v_add_u32_e32 v51, 0x2000, v26
	ds_read2_b32 v[54:55], v26 offset0:16 offset1:24
	ds_read2_b32 v[56:57], v27 offset1:8
	ds_read2_b32 v[58:59], v51 offset1:8
	ds_read2_b32 v[60:61], v68 offset1:8
	ds_read2_b32 v[62:63], v70 offset1:8
	ds_read2_b32 v[64:65], v27 offset0:16 offset1:24
	ds_read2_b32 v[66:67], v51 offset0:16 offset1:24
	ds_read2_b32 v[68:69], v68 offset0:16 offset1:24
	ds_read2_b32 v[70:71], v70 offset0:16 offset1:24
	s_waitcnt lgkmcnt(9)
	v_mov_b32_e32 v72, v53
	s_waitcnt lgkmcnt(7)
	v_mov_b32_e32 v76, v57
	s_waitcnt lgkmcnt(6)
	v_mov_b32_e32 v78, v59
	s_waitcnt lgkmcnt(5)
	v_mov_b32_e32 v80, v61
	s_waitcnt lgkmcnt(4)
	v_mov_b32_e32 v82, v63
	v_mov_b32_e32 v74, v55
	s_waitcnt lgkmcnt(3)
	v_mov_b32_e32 v84, v65
	s_waitcnt lgkmcnt(2)
	v_mov_b32_e32 v86, v67
	s_waitcnt lgkmcnt(1)
	v_mov_b32_e32 v88, v69
	s_waitcnt lgkmcnt(0)
	v_mov_b32_e32 v90, v71
	v_add_u32_e32 v26, 0x80, v26
	s_waitcnt vmcnt(3)
	v_pk_fma_f32 v[24:25], v[140:141], v[52:53], v[24:25] op_sel_hi:[1,0,1]
	v_pk_fma_f32 v[22:23], v[142:143], v[52:53], v[22:23] op_sel_hi:[1,0,1]
	v_pk_fma_f32 v[18:19], v[140:141], v[56:57], v[18:19] op_sel_hi:[1,0,1]
	v_pk_fma_f32 v[16:17], v[142:143], v[56:57], v[16:17] op_sel_hi:[1,0,1]
	v_pk_fma_f32 v[14:15], v[140:141], v[58:59], v[14:15] op_sel_hi:[1,0,1]
	v_pk_fma_f32 v[12:13], v[142:143], v[58:59], v[12:13] op_sel_hi:[1,0,1]
	v_pk_fma_f32 v[10:11], v[140:141], v[60:61], v[10:11] op_sel_hi:[1,0,1]
	v_pk_fma_f32 v[8:9], v[142:143], v[60:61], v[8:9] op_sel_hi:[1,0,1]
	v_pk_fma_f32 v[6:7], v[140:141], v[62:63], v[6:7] op_sel_hi:[1,0,1]
	v_pk_fma_f32 v[4:5], v[142:143], v[62:63], v[4:5] op_sel_hi:[1,0,1]
	s_waitcnt vmcnt(2)
	v_pk_fma_f32 v[22:23], v[146:147], v[72:73], v[22:23] op_sel_hi:[1,0,1]
	v_pk_fma_f32 v[24:25], v[144:145], v[72:73], v[24:25] op_sel_hi:[1,0,1]
	v_pk_fma_f32 v[16:17], v[146:147], v[76:77], v[16:17] op_sel_hi:[1,0,1]
	v_pk_fma_f32 v[18:19], v[144:145], v[76:77], v[18:19] op_sel_hi:[1,0,1]
	v_pk_fma_f32 v[12:13], v[146:147], v[78:79], v[12:13] op_sel_hi:[1,0,1]
	v_pk_fma_f32 v[14:15], v[144:145], v[78:79], v[14:15] op_sel_hi:[1,0,1]
	v_pk_fma_f32 v[8:9], v[146:147], v[80:81], v[8:9] op_sel_hi:[1,0,1]
	v_pk_fma_f32 v[10:11], v[144:145], v[80:81], v[10:11] op_sel_hi:[1,0,1]
	v_pk_fma_f32 v[4:5], v[146:147], v[82:83], v[4:5] op_sel_hi:[1,0,1]
	v_pk_fma_f32 v[6:7], v[144:145], v[82:83], v[6:7] op_sel_hi:[1,0,1]
	s_waitcnt vmcnt(1)
	v_pk_fma_f32 v[24:25], v[148:149], v[54:55], v[24:25] op_sel_hi:[1,0,1]
	v_pk_fma_f32 v[22:23], v[150:151], v[54:55], v[22:23] op_sel_hi:[1,0,1]
	v_pk_fma_f32 v[18:19], v[148:149], v[64:65], v[18:19] op_sel_hi:[1,0,1]
	v_pk_fma_f32 v[16:17], v[150:151], v[64:65], v[16:17] op_sel_hi:[1,0,1]
	v_pk_fma_f32 v[14:15], v[148:149], v[66:67], v[14:15] op_sel_hi:[1,0,1]
	v_pk_fma_f32 v[12:13], v[150:151], v[66:67], v[12:13] op_sel_hi:[1,0,1]
	v_pk_fma_f32 v[10:11], v[148:149], v[68:69], v[10:11] op_sel_hi:[1,0,1]
	v_pk_fma_f32 v[8:9], v[150:151], v[68:69], v[8:9] op_sel_hi:[1,0,1]
	v_pk_fma_f32 v[6:7], v[148:149], v[70:71], v[6:7] op_sel_hi:[1,0,1]
	v_pk_fma_f32 v[4:5], v[150:151], v[70:71], v[4:5] op_sel_hi:[1,0,1]
	s_waitcnt vmcnt(0)
	v_pk_fma_f32 v[22:23], v[154:155], v[74:75], v[22:23] op_sel_hi:[1,0,1]
	v_pk_fma_f32 v[24:25], v[152:153], v[74:75], v[24:25] op_sel_hi:[1,0,1]
	v_pk_fma_f32 v[16:17], v[154:155], v[84:85], v[16:17] op_sel_hi:[1,0,1]
	v_pk_fma_f32 v[18:19], v[152:153], v[84:85], v[18:19] op_sel_hi:[1,0,1]
	v_pk_fma_f32 v[12:13], v[154:155], v[86:87], v[12:13] op_sel_hi:[1,0,1]
	v_pk_fma_f32 v[14:15], v[152:153], v[86:87], v[14:15] op_sel_hi:[1,0,1]
	v_pk_fma_f32 v[8:9], v[154:155], v[88:89], v[8:9] op_sel_hi:[1,0,1]
	v_pk_fma_f32 v[10:11], v[152:153], v[88:89], v[10:11] op_sel_hi:[1,0,1]
	v_pk_fma_f32 v[4:5], v[154:155], v[90:91], v[4:5] op_sel_hi:[1,0,1]
	v_pk_fma_f32 v[6:7], v[152:153], v[90:91], v[6:7] op_sel_hi:[1,0,1]

	ds_bpermute_b32 v20, v3, v24
	ds_bpermute_b32 v21, v3, v25
	ds_bpermute_b32 v26, v3, v22
	ds_bpermute_b32 v27, v3, v23
	ds_bpermute_b32 v36, v3, v10
	ds_bpermute_b32 v37, v3, v11
	s_waitcnt lgkmcnt(4)
	v_pk_add_f32 v[20:21], v[24:25], v[20:21]
	ds_bpermute_b32 v24, v45, v20
	s_waitcnt lgkmcnt(3)
	v_pk_add_f32 v[26:27], v[22:23], v[26:27]
	ds_bpermute_b32 v25, v45, v21
	ds_bpermute_b32 v28, v45, v26
	ds_bpermute_b32 v29, v45, v27
	ds_bpermute_b32 v30, v3, v18
	ds_bpermute_b32 v31, v3, v19
	s_waitcnt lgkmcnt(6)
	v_pk_add_f32 v[10:11], v[10:11], v[36:37]
	s_waitcnt lgkmcnt(4)
	v_pk_add_f32 v[20:21], v[20:21], v[24:25]
	s_waitcnt lgkmcnt(2)
	v_pk_add_f32 v[24:25], v[26:27], v[28:29]
	ds_bpermute_b32 v32, v3, v14
	s_waitcnt lgkmcnt(1)
	v_pk_add_f32 v[26:27], v[18:19], v[30:31]
	ds_bpermute_b32 v30, v3, v16
	ds_bpermute_b32 v31, v3, v17
	ds_bpermute_b32 v33, v3, v15
	ds_bpermute_b32 v34, v3, v12
	ds_bpermute_b32 v35, v3, v13
	ds_bpermute_b32 v36, v45, v10
	ds_bpermute_b32 v37, v45, v11
	ds_bpermute_b32 v38, v3, v8
	ds_bpermute_b32 v39, v3, v9
	ds_bpermute_b32 v40, v3, v6
	ds_bpermute_b32 v41, v3, v7
	ds_bpermute_b32 v42, v3, v4
	ds_bpermute_b32 v43, v3, v5
	s_waitcnt lgkmcnt(11)
	v_pk_add_f32 v[16:17], v[16:17], v[30:31]
	s_waitcnt lgkmcnt(10)
	v_pk_add_f32 v[14:15], v[14:15], v[32:33]
	s_waitcnt lgkmcnt(8)
	v_pk_add_f32 v[12:13], v[12:13], v[34:35]
	s_waitcnt lgkmcnt(6)
	v_pk_add_f32 v[10:11], v[10:11], v[36:37]
	s_waitcnt lgkmcnt(4)
	v_pk_add_f32 v[36:37], v[8:9], v[38:39]
	s_waitcnt lgkmcnt(2)
	v_pk_add_f32 v[6:7], v[6:7], v[40:41]
	s_waitcnt lgkmcnt(0)
	v_pk_add_f32 v[42:43], v[4:5], v[42:43]
	ds_bpermute_b32 v28, v45, v26
	ds_bpermute_b32 v29, v45, v27
	ds_bpermute_b32 v30, v45, v16
	ds_bpermute_b32 v31, v45, v17
	ds_bpermute_b32 v32, v45, v14
	ds_bpermute_b32 v33, v45, v15
	ds_bpermute_b32 v34, v45, v12
	ds_bpermute_b32 v35, v45, v13
	ds_bpermute_b32 v38, v45, v36
	ds_bpermute_b32 v39, v45, v37
	ds_bpermute_b32 v40, v45, v6
	ds_bpermute_b32 v41, v45, v7
	ds_bpermute_b32 v52, v45, v42
	ds_bpermute_b32 v53, v45, v43
	s_waitcnt lgkmcnt(12)
	v_pk_add_f32 v[26:27], v[26:27], v[28:29]
	s_waitcnt lgkmcnt(10)
	v_pk_add_f32 v[16:17], v[16:17], v[30:31]
	s_waitcnt lgkmcnt(8)
	v_pk_add_f32 v[14:15], v[14:15], v[32:33]
	s_waitcnt lgkmcnt(6)
	v_pk_add_f32 v[12:13], v[12:13], v[34:35]
	s_waitcnt lgkmcnt(4)
	v_pk_add_f32 v[36:37], v[36:37], v[38:39]
	s_waitcnt lgkmcnt(2)
	v_pk_add_f32 v[4:5], v[6:7], v[40:41]
	s_waitcnt lgkmcnt(0)
	v_pk_add_f32 v[40:41], v[42:43], v[52:53]
	ds_bpermute_b32 v22, v46, v20
	ds_bpermute_b32 v23, v46, v21
	ds_bpermute_b32 v18, v46, v24
	ds_bpermute_b32 v19, v46, v25
	ds_bpermute_b32 v28, v46, v26
	ds_bpermute_b32 v29, v46, v27
	ds_bpermute_b32 v30, v46, v16
	ds_bpermute_b32 v31, v46, v17
	ds_bpermute_b32 v32, v46, v14
	ds_bpermute_b32 v33, v46, v15
	ds_bpermute_b32 v34, v46, v12
	ds_bpermute_b32 v35, v46, v13
	ds_bpermute_b32 v8, v46, v10
	ds_bpermute_b32 v9, v46, v11
	ds_bpermute_b32 v38, v46, v36
	ds_bpermute_b32 v39, v46, v37
	ds_bpermute_b32 v6, v46, v4
	ds_bpermute_b32 v7, v46, v5
	ds_bpermute_b32 v42, v46, v40
	ds_bpermute_b32 v43, v46, v41
	s_and_saveexec_b64 s[2:3], s[38:39]
	s_cbranch_execz .Lal_1108

	s_waitcnt lgkmcnt(14)
	v_pk_add_f32 v[20:21], v[20:21], v[22:23]
	v_pk_add_f32 v[22:23], v[24:25], v[18:19]
	ds_write_b128 v49, v[20:23] offset:20480
	v_pk_add_f32 v[18:19], v[26:27], v[28:29]
	s_waitcnt lgkmcnt(13)
	v_pk_add_f32 v[20:21], v[16:17], v[30:31]
	s_waitcnt lgkmcnt(11)
	v_pk_add_f32 v[14:15], v[14:15], v[32:33]
	s_waitcnt lgkmcnt(9)
	v_pk_add_f32 v[16:17], v[12:13], v[34:35]
	s_waitcnt lgkmcnt(7)
	v_pk_add_f32 v[8:9], v[10:11], v[8:9]
	s_waitcnt lgkmcnt(5)
	v_pk_add_f32 v[10:11], v[36:37], v[38:39]
	s_waitcnt lgkmcnt(3)
	v_pk_add_f32 v[4:5], v[4:5], v[6:7]
	s_waitcnt lgkmcnt(1)
	v_pk_add_f32 v[6:7], v[40:41], v[42:43]
	ds_write_b128 v49, v[18:21] offset:20608
	ds_write_b128 v49, v[14:17] offset:20736
	ds_write_b128 v49, v[8:11] offset:20864
	ds_write_b128 v49, v[4:7] offset:20992
.Lal_1108:
	s_or_b64 exec, exec, s[2:3]
	s_waitcnt lgkmcnt(0)
	s_barrier
	s_and_saveexec_b64 s[2:3], s[40:41]
	s_cbranch_execz .Lal_1110

	s_mul_i32 s23, s21, 0x1800
	s_add_i32 s23, s23, s0
	v_or_b32_e32 v4, s23, v2
	v_ashrrev_i32_e32 v5, 31, v4
	v_lshl_add_u64 v[4:5], v[4:5], 2, s[18:19]
	global_load_dword v18, v[4:5], off
	v_add_u32_e32 v10, 0x5000, v50
	v_add_u32_e32 v12, 0x5400, v50
	v_add_u32_e32 v14, 0x5a00, v50
	v_add_u32_e32 v16, 0x5e00, v50
	v_mad_i64_i32 v[4:5], s[34:35], s21, 5, v[0:1]
	v_mov_b64_e32 v[6:7], s[36:37]
	ds_read2_b32 v[10:11], v10 offset1:160
	ds_read2_b32 v[12:13], v12 offset0:64 offset1:224
	ds_read2_b32 v[14:15], v14 offset1:160
	ds_read2_b32 v[16:17], v16 offset0:64 offset1:224
	v_mad_u64_u32 v[6:7], s[34:35], v4, s25, v[6:7]
	v_mad_i32_i24 v7, v5, s25, v7
	v_lshl_add_u64 v[4:5], s[0:1], 2, v[6:7]
	s_waitcnt lgkmcnt(3)
	v_add_f32_e32 v6, 0, v10
	v_add_f32_e32 v6, v6, v11
	s_waitcnt lgkmcnt(2)
	v_add_f32_e32 v6, v6, v12
	v_add_f32_e32 v6, v6, v13
	s_waitcnt lgkmcnt(1)
	v_add_f32_e32 v6, v6, v14
	v_add_f32_e32 v6, v6, v15
	s_waitcnt lgkmcnt(0)
	v_add_f32_e32 v6, v6, v16
	v_lshlrev_b32_e32 v8, 2, v2
	v_mov_b32_e32 v9, v179
	v_add_f32_e32 v6, v6, v17
	v_lshl_add_u64 v[4:5], v[4:5], 0, v[8:9]
	s_waitcnt vmcnt(0)
	v_add_f32_e32 v6, v6, v18
	global_store_dword v[4:5], v6, off
.Lal_1110:
	s_or_b64 exec, exec, s[2:3]
	s_add_i32 s0, s22, 0xbf
	s_cmpk_lt_u32 s0, 0x17f
	s_cselect_b64 s[0:1], -1, 0
	s_cmp_lt_i32 s20, 64
	s_waitcnt vmcnt(0)
	s_cselect_b64 s[2:3], -1, 0
	s_and_b64 s[0:1], s[0:1], s[2:3]
	s_and_b64 s[0:1], vcc, s[0:1]
	s_barrier
	s_and_saveexec_b64 s[2:3], s[0:1]
	s_cbranch_execz .Lal_1103

	s_mov_b64 s[20:21], exec
	v_mbcnt_lo_u32_b32 v4, s20, 0
	v_mbcnt_hi_u32_b32 v4, s21, v4
	v_cmp_eq_u32_e64 s[0:1], 0, v4
	s_and_b64 s[0:1], exec, s[0:1]
	buffer_wbl2 sc1
	s_waitcnt vmcnt(0)
	s_mov_b64 exec, s[0:1]
	s_cbranch_execz .Lal_1103

	s_bcnt1_i32_b64 s0, s[20:21]
	v_mov_b32_e32 v4, s0
	global_atomic_add v179, v4, s[44:45]
	s_branch .Lal_1103
.Lal_exit:
	s_waitcnt vmcnt(0) lgkmcnt(0)
	s_barrier
	v_readlane_b32 s0, v255, 24
	v_readlane_b32 s1, v255, 25
	v_readlane_b32 s2, v255, 26
	v_readlane_b32 s3, v255, 27
	v_readlane_b32 s20, v255, 28
	v_readlane_b32 s21, v255, 29
	v_readlane_b32 s22, v255, 30
	v_readlane_b32 s23, v255, 31
	v_readlane_b32 s26, v255, 32
	v_readlane_b32 s34, v255, 33
	v_readlane_b32 s35, v255, 34
	v_readlane_b32 s36, v255, 35
	v_readlane_b32 s37, v255, 36
	v_readlane_b32 s38, v255, 37
	v_readlane_b32 s39, v255, 38
	v_readlane_b32 s40, v255, 39
	v_readlane_b32 s41, v255, 40
	v_readlane_b32 s44, v255, 41
	v_readlane_b32 s45, v255, 42
	v_readlane_b32 s56, v255, 43
	s_nop 4
